# forget-gate cumsum moved to the workgroups that have one fewer projection tile
# baseline (speedup 1.0000x reference)
; __device__ __forceinline__ void cumsum_seq(const float* LOGF, float* CUM, int seq, int lane) {
;     const int b = seq >> 2, h = seq & 3; const size_t base = ((size_t)b * SEQ + 32 * lane) * 4 + h;
;     float s = 0.f;
; #pragma unroll 8
;     for (int i = 0; i < 32; ++i) s += LOGF[base + 4 * i];
;     float incl = s;
; #pragma unroll
;     for (int o = 1; o < 64; o <<= 1) { const float n = __shfl_up(incl, o); if (lane >= o) incl += n; }
; __global__ void __launch_bounds__(NTHREADS, 2) mega(Args a_) {
;     ...
;             if (half == 0 && wave == 0) { for (int q = bid; q < NB * 4; q += G) cumsum_seq(LOGF, CUM, q, lane); }
;             pg8::Gemm g{U + (size_t)half * MH * DM, (const bf16_t*)(wsw + W_IN), MH, NPROJ, DM}; pg8::StaticOrder S; S.init(MH, NPROJ, G, bid);
.LBB0_465:
	v_mov_b32_e32 v0, v228
	s_cmp_lg_u32 s0, 7
	s_cselect_b64 s[20:21], -1, 0
	v_readfirstlane_b32 s1, v0
	s_cmp_lt_u32 s1, 64
	s_mov_b32 s46, s2
	s_cselect_b64 s[6:7], -1, 0
	s_load_dword s47, s[90:91], 0x0
	s_and_b64 s[6:7], s[20:21], s[6:7]
	s_waitcnt lgkmcnt(0)
	s_mov_b32 s3, s46
	s_cmpk_lt_u32 s47, 0x100
	s_cbranch_scc1 .Lcs_noshift
	s_add_i32 s3, s46, 0xffffff80
.Lcs_noshift:
	s_cmpk_lt_u32 s3, 0x80
	s_cselect_b64 s[8:9], -1, 0
	s_and_b64 s[6:7], s[6:7], s[8:9]
	s_andn2_b64 vcc, exec, s[6:7]
	s_cbranch_vccnz .LBB0_472
	v_and_b32_e32 v2, 64, v231
	v_add_u32_e32 v3, -1, v231
	v_cmp_lt_i32_e32 vcc, v3, v2
	v_and_b32_e32 v0, 63, v0
	v_cmp_eq_u32_e64 s[6:7], 0, v0
	v_cndmask_b32_e32 v3, v3, v231, vcc
	v_lshlrev_b32_e32 v6, 2, v3
	v_add_u32_e32 v3, -2, v231
	v_cmp_lt_i32_e32 vcc, v3, v2
	v_cmp_gt_u32_e64 s[8:9], 2, v0
	v_cmp_gt_u32_e64 s[10:11], 4, v0
	v_cndmask_b32_e32 v3, v3, v231, vcc
	v_lshlrev_b32_e32 v7, 2, v3
	v_add_u32_e32 v3, -4, v231
	v_cmp_lt_i32_e32 vcc, v3, v2
	v_cmp_gt_u32_e64 s[12:13], 8, v0
	v_cmp_gt_u32_e64 s[14:15], 16, v0
	v_cndmask_b32_e32 v3, v3, v231, vcc
	v_lshlrev_b32_e32 v8, 2, v3
	v_add_u32_e32 v3, -8, v231
	v_cmp_lt_i32_e32 vcc, v3, v2
	v_cmp_gt_u32_e64 s[16:17], 32, v0
	v_lshlrev_b32_e32 v0, 9, v0
	v_cndmask_b32_e32 v3, v3, v231, vcc
	v_lshlrev_b32_e32 v9, 2, v3
	v_add_u32_e32 v3, -16, v231
	v_cmp_lt_i32_e32 vcc, v3, v2
	s_mov_b32 s1, s3
	s_waitcnt lgkmcnt(0)
	v_cndmask_b32_e32 v3, v3, v231, vcc
	v_lshlrev_b32_e32 v10, 2, v3
	v_subrev_u32_e32 v3, 32, v231
	v_cmp_lt_i32_e32 vcc, v3, v2
	s_nop 1
	v_cndmask_b32_e32 v2, v3, v231, vcc
	v_lshlrev_b32_e32 v11, 2, v2
	v_lshl_add_u64 v[2:3], s[26:27], 0, v[0:1]
